# loop-edge rotation: attention loop-control block moved in front of the closing barrier
# speedup vs baseline: 1.0445x; 1.0034x over previous
.Latt_swa_w_d:
	s_add_i32 s28, s45, 1
	s_cmp_lg_u32 s45, 2
	s_cselect_b32 s28, s28, 0
	s_add_i32 s47, s47, 1
	s_add_i32 s43, s43, 64
	s_cmp_ge_i32 s47, s41
	s_mov_b32 s48, s46
	s_mov_b32 s46, s45
	s_mov_b32 s45, s28
	s_waitcnt lgkmcnt(0)
	s_barrier
	s_cbranch_scc1 .LBB0_37
	s_branch .LBB0_57

.Latt_diff_w_d:
	s_add_i32 s30, s50, 1
	s_cmp_lg_u32 s50, 2
	s_cselect_b32 s46, s30, 0
	s_add_i32 s52, s52, 1
	s_add_i32 s43, s43, 64
	s_add_i32 s45, s45, 64
	s_cmp_eq_u32 s21, s52
	s_mov_b32 s53, s51
	s_mov_b32 s51, s50
	s_mov_b32 s50, s46
	s_waitcnt lgkmcnt(0)
	s_barrier
	s_cbranch_scc1 .LBB0_88
	s_branch .LBB0_107

.Latt_mla_w_d:
	s_add_i32 s30, s52, 1
	s_cmp_lg_u32 s52, 2
	s_cselect_b32 s57, s30, 0
	s_add_i32 s55, s55, 1
	s_add_i32 s49, s49, 64
	s_add_i32 s51, s51, 64
	s_cmp_eq_u32 s20, s55
	s_mov_b32 s56, s53
	s_mov_b32 s53, s52
	s_mov_b32 s52, s57
	s_waitcnt lgkmcnt(0)
	s_barrier
	s_cbranch_scc1 .LBB0_153
	s_branch .LBB0_178
